# even layers: PE GEMM tiles split 1/3 between WGs that had 5/4 in-proj tiles (load balance of the G3 phase)
# speedup vs baseline: 1.0009x; 1.0009x over previous
;   __device__ __forceinline__ bool next(int it, Unit& u) const {
;     int wg;
;     if (remap) {
;       int li = it * spx + off;
;       if (li >= qx) return false;
;       wg = xcd * qx + li;
;     } else {
;       wg = it * (int)gridDim.x + (int)blockIdx.x;
;       if (wg >= nwg) return false;
;     }
;     const int nig = 8 * nN, gid = wg / nig, fm = gid * 8, gsz = (nM - fm) < 8 ? (nM - fm) : 8;
;     u.pm = fm + ((wg % nig) % gsz);
;     u.pn = (wg % nig) / gsz;
;     return true;
; template <int CLS>
; __device__ __forceinline__ void run_phase(const Params& P, int l, int kind_in, const int wid) {
;     ...
;           EpiArgs eb{};
;           eb.out_bf = pe;
;           eb.aux_f1 = P.in[I_PLEN] + l * 1024;
;           eb.ss_out = dup ? c2 : sspe + (size_t)l * T;
;     ...
;           gemm_phase<EPI_PE>(pbf, reinterpret_cast<const u16*>(ws + OFF_W_PLE + (size_t)l * 1024 * 256 * 2), T, 1024, 256, eb, wid);
.LBB0_795:
	v_readlane_b32 s4, v251, 43
	v_readlane_b32 s1, v251, 58
	v_readlane_b32 s5, v251, 44
	v_readlane_b32 s6, v255, 42
	s_bitcmp1_b32 s6, 0
	s_cbranch_scc1 .Lpe_first_done
	s_cmp_eq_u32 s21, 32
	s_cbranch_scc0 .Lpe_first_done
	s_cmp_lt_u32 s96, 16
	s_cbranch_scc1 .Lpe_first_done
	s_mul_i32 s6, s96, 3
	s_add_i32 s6, s6, -32
	s_and_b32 s1, s1, 0xffffffc0
	s_or_b32 s1, s1, s6
.Lpe_first_done:
.LBB0_796:
	s_andn2_b64 vcc, exec, s[4:5]
	s_mov_b64 s[4:5], 0
	s_cbranch_vccnz .LBB0_798
	s_ashr_i32 s2, s1, 31
	s_lshr_b32 s2, s2, 27
	s_add_i32 s2, s1, s2
	s_ashr_i32 s4, s2, 5
	s_and_b32 s2, s2, 0xffe0
	s_sub_i32 s1, s1, s2
	s_bfe_i32 s2, s1, 0x80000
	s_bfe_u32 s2, s2, 0x3000c
	s_add_i32 s2, s1, s2
	s_bfe_i32 s5, s2, 0x80000
	s_and_b32 s2, s2, 0xf8
	s_sub_i32 s1, s1, s2
	s_lshl_b32 s4, s4, 3
	s_sext_i32_i16 s5, s5
	s_sext_i32_i8 s1, s1
	s_add_i32 s66, s4, s1
	s_ashr_i32 s68, s5, 3
	s_branch .LBB0_799

;   __device__ __forceinline__ bool next(int it, Unit& u) const {
;     int wg;
;     if (remap) {
;       int li = it * spx + off;
;       if (li >= qx) return false;
;       wg = xcd * qx + li;
;     } else {
;       wg = it * (int)gridDim.x + (int)blockIdx.x;
;       if (wg >= nwg) return false;
;     }
;     const int nig = 8 * nN, gid = wg / nig, fm = gid * 8, gsz = (nM - fm) < 8 ? (nM - fm) : 8;
;     u.pm = fm + ((wg % nig) % gsz);
;     u.pn = (wg % nig) / gsz;
;     return true;
;     ...
;       const bool has_next = S.next(ui + 1, nxt);
;       const char* nA = has_next ? (const char*)Ag + (size_t)nxt.pm * tstep : cA;
;       const char* nB = has_next ? (const char*)Btg + (size_t)nxt.pn * tstep : cB;
.LBB0_806:
	v_readlane_b32 s52, v255, 42
	s_bitcmp1_b32 s52, 0
	s_cbranch_scc1 .Lpe_next_orig
	s_cmp_eq_u32 s21, 32
	s_cbranch_scc0 .Lpe_next_orig
	s_cmp_lt_u32 s96, 16
	s_cbranch_scc1 .LBB0_808
	s_cmp_lt_u32 s56, 3
	s_cbranch_scc0 .LBB0_808
	s_mul_i32 s52, s96, 3
	s_add_i32 s52, s52, -32
	s_add_i32 s52, s52, s56
	v_readlane_b32 s10, v252, 56
	s_or_b32 s23, s52, s10
	s_mov_b64 s[10:11], -1
	s_branch .LBB0_808
